# batch in-stream top-k prunes: when any candidate list exceeds 640, also prune lists above 544 in the same round so all four waves work
# speedup vs baseline: 1.0287x; 1.0287x over previous
.Lrd_app7:
.LBB0_138:
	s_or_b64 exec, exec, s[2:3]
	s_waitcnt lgkmcnt(0)
	s_barrier
	s_mov_b64 s[2:3], 0
	s_and_saveexec_b64 s[6:7], s[4:5]
	s_cbranch_execz .LBB0_140
	ds_read_b32 v40, v157
	s_movk_i32 s2, 0x280
	s_waitcnt lgkmcnt(0)
	v_cmp_lt_i32_e32 vcc, s2, v40
	s_and_b64 s[2:3], vcc, exec
	s_cmp_eq_u64 s[2:3], 0
	s_cbranch_scc1 .LBB0_140
	s_movk_i32 s2, 544
	v_cmp_lt_i32_e32 vcc, s2, v40
	s_and_b64 s[2:3], vcc, exec
